# up GEMM K-loop: rebalance LDS-DMA issue between load segments (two A-tile pieces moved from the 6-DMA segment to the next 2-DMA segment, wait count re-derived)
# speedup vs baseline: 1.0050x; 1.0023x over previous
; #define PG8_STAGE(bufoff, gbase, voff) do { _Pragma("unroll") for (int _i = 0; _i < 2; ++_i) \
;         __builtin_amdgcn_global_load_lds((const unsigned*)((const char*)(gbase) + (voff)[_i]), (PG8_LAS unsigned*)(lds + (bufoff) + ldsw + _i * 8192), 16, 0, 0); } while (0)
; #define PG8_LDA(dst, b, h) do { _Pragma("unroll") for (int m = 0; m < 4; ++m) _Pragma("unroll") for (int k = 0; k < 2; ++k) dst[m][k] = *(const PG8_LAS bf16x8*)(lds + PG8_SA(b, h) + aoff + m * 2048 + k * 1024); } while (0)
; #define PG8_LDB(dst, b, h) do { _Pragma("unroll") for (int n = 0; n < 2; ++n) _Pragma("unroll") for (int k = 0; k < 2; ++k) dst[n][k] = *(const PG8_LAS bf16x8*)(lds + PG8_SB(b, h) + boff + n * 2048 + k * 1024); } while (0)
; #define PG8_MMA(ai, bj, At, Bt) do { __builtin_amdgcn_s_setprio(1); _Pragma("unroll") for (int m = 0; m < 4; ++m) _Pragma("unroll") for (int n = 0; n < 2; ++n) _Pragma("unroll") for (int k = 0; k < 2; ++k) \
;         acc[ai][bj][m][n] = __builtin_amdgcn_mfma_f32_16x16x32_bf16(Bt[n][k], At[m][k], acc[ai][bj][m][n], 0, 0, 0); __builtin_amdgcn_s_setprio(0); } while (0)
; #define PG8_WAIT_V(n) asm volatile("s_waitcnt vmcnt(" #n ")" ::: "memory")
; #define PG8_WAIT_L(n) asm volatile("s_waitcnt lgkmcnt(" #n ")" ::: "memory")
; #define PG8_BAR __builtin_amdgcn_s_barrier()
; #define PG8_SCHED __builtin_amdgcn_sched_barrier(0)
; template <class Epi, class Sched, bool ALIGN_EPI = false, bool SP2 = false, bool HALO = false>
; __device__ __forceinline__ void gemm_phase(PG8_LAS unsigned char* lds, const Gemm g, const Sched& S, const Epi& E, const int wave0) {
;     ...
;             PG8_LDB(B0, 0, 0); PG8_LDB(B1, 0, 1); PG8_SCHED; PG8_LDA(At, 0, 0); PG8_STAGE(PG8_SA(1, 1), a1 + hstepA, voffA);
;             PG8_WAIT_V(8); PG8_WAIT_L(0); PG8_BAR; PG8_MMA(0, 0, At, B0); PG8_MMA(0, 1, At, B1); PG8_BAR; PG8_SCHED;
;             PG8_LDA(At, 0, 1); PG8_STAGE(PG8_SB(0, 0), b2, voffB); PG8_STAGE(PG8_SB(0, 1), b2 + hstep, voffB); PG8_STAGE(PG8_SA(0, 0), a2, voffA);
;             PG8_WAIT_V(8); PG8_WAIT_L(0); PG8_BAR; PG8_MMA(1, 0, At, B0); PG8_MMA(1, 1, At, B1); PG8_BAR; PG8_SCHED;
.LBB0_1081:
	s_add_u32 s80, s48, 0xfffc2080
	s_addc_u32 s81, s49, -1
	s_add_i32 s82, 0, 0x10000
	s_cmp_eq_u32 s78, 12
	s_cselect_b32 s85, s75, s81
	s_cselect_b32 s84, s74, s80
	s_cselect_b32 s81, s53, vcc_hi
	s_cselect_b32 s80, s73, vcc_lo
	s_add_i32 s79, 0, 0x14000
	v_add_u32_e32 v68, s82, v173
	v_add_u32_e32 v92, s79, v173
	ds_read_b128 v[56:59], v68
	ds_read_b128 v[60:63], v68 offset:1024
	ds_read_b128 v[64:67], v68 offset:2048
	ds_read_b128 v[68:71], v68 offset:3072
	ds_read_b128 v[76:79], v92
	ds_read_b128 v[80:83], v92 offset:1024
	ds_read_b128 v[84:87], v92 offset:2048
	ds_read_b128 v[92:95], v92 offset:3072
	v_lshl_add_u64 v[170:171], s[48:49], 0, v[168:169]
	s_add_i32 m0, s90, 0xc000
	ds_read_b128 v[180:183], v178
	ds_read_b128 v[184:187], v178 offset:1024
	ds_read_b128 v[188:191], v178 offset:2048
	ds_read_b128 v[192:195], v178 offset:3072
	ds_read_b128 v[196:199], v178 offset:4096
	ds_read_b128 v[200:203], v178 offset:5120
	ds_read_b128 v[204:207], v178 offset:6144
	ds_read_b128 v[210:213], v178 offset:7168
	global_load_lds_dwordx4 v[170:171], off
	v_lshl_add_u64 v[170:171], s[48:49], 0, v[166:167]
	s_add_i32 m0, s90, 0xe000
	s_nop 0
	global_load_lds_dwordx4 v[170:171], off
	s_waitcnt vmcnt(8)
	s_waitcnt lgkmcnt(0)
	s_barrier
	s_setprio 1
	s_waitcnt lgkmcnt(0)
	v_mfma_f32_16x16x32_bf16 v[152:155], v[56:59], v[180:183], v[152:155]
	v_mfma_f32_16x16x32_bf16 v[156:159], v[64:67], v[180:183], v[156:159]
	v_mfma_f32_16x16x32_bf16 v[140:143], v[56:59], v[188:191], v[140:143]
	v_mfma_f32_16x16x32_bf16 v[136:139], v[64:67], v[188:191], v[136:139]
	v_mfma_f32_16x16x32_bf16 v[124:127], v[56:59], v[196:199], v[124:127]
	v_mfma_f32_16x16x32_bf16 v[120:123], v[64:67], v[196:199], v[120:123]
	v_mfma_f32_16x16x32_bf16 v[108:111], v[56:59], v[204:207], v[108:111]
	v_mfma_f32_16x16x32_bf16 v[104:107], v[64:67], v[204:207], v[104:107]
	v_mfma_f32_16x16x32_bf16 v[152:155], v[60:63], v[184:187], v[152:155]
	v_mfma_f32_16x16x32_bf16 v[156:159], v[68:71], v[184:187], v[156:159]
	v_mfma_f32_16x16x32_bf16 v[140:143], v[60:63], v[192:195], v[140:143]
	v_mfma_f32_16x16x32_bf16 v[136:139], v[68:71], v[192:195], v[136:139]
	v_mfma_f32_16x16x32_bf16 v[124:127], v[60:63], v[200:203], v[124:127]
	v_mfma_f32_16x16x32_bf16 v[120:123], v[68:71], v[200:203], v[120:123]
	v_mfma_f32_16x16x32_bf16 v[108:111], v[60:63], v[210:213], v[108:111]
	v_mfma_f32_16x16x32_bf16 v[104:107], v[68:71], v[210:213], v[104:107]
	s_setprio 0
	s_setprio 1
	v_mfma_f32_16x16x32_bf16 v[148:151], v[76:79], v[180:183], v[148:151]
	v_mfma_f32_16x16x32_bf16 v[144:147], v[84:87], v[180:183], v[144:147]
	v_mfma_f32_16x16x32_bf16 v[132:135], v[76:79], v[188:191], v[132:135]
	v_mfma_f32_16x16x32_bf16 v[128:131], v[84:87], v[188:191], v[128:131]
	v_mfma_f32_16x16x32_bf16 v[116:119], v[76:79], v[196:199], v[116:119]
	v_mfma_f32_16x16x32_bf16 v[112:115], v[84:87], v[196:199], v[112:115]
	v_mfma_f32_16x16x32_bf16 v[100:103], v[76:79], v[204:207], v[100:103]
	v_mfma_f32_16x16x32_bf16 v[96:99], v[84:87], v[204:207], v[96:99]
	v_mfma_f32_16x16x32_bf16 v[148:151], v[80:83], v[184:187], v[148:151]
	v_mfma_f32_16x16x32_bf16 v[144:147], v[92:95], v[184:187], v[144:147]
	v_mfma_f32_16x16x32_bf16 v[132:135], v[80:83], v[192:195], v[132:135]
	v_mfma_f32_16x16x32_bf16 v[128:131], v[92:95], v[192:195], v[128:131]
	v_mfma_f32_16x16x32_bf16 v[116:119], v[80:83], v[200:203], v[116:119]
	v_mfma_f32_16x16x32_bf16 v[112:115], v[92:95], v[200:203], v[112:115]
	v_mfma_f32_16x16x32_bf16 v[100:103], v[80:83], v[210:213], v[100:103]
	v_mfma_f32_16x16x32_bf16 v[96:99], v[92:95], v[210:213], v[96:99]
	s_setprio 0
	s_barrier
	s_add_i32 s82, s82, s89
	v_lshl_add_u64 v[170:171], s[80:81], 0, v[208:209]
	s_mov_b32 m0, s82
	ds_read_b128 v[180:183], v178 offset:16384
	ds_read_b128 v[184:187], v178 offset:17408
	ds_read_b128 v[188:191], v178 offset:18432
	ds_read_b128 v[192:195], v178 offset:19456
	ds_read_b128 v[196:199], v178 offset:20480
	ds_read_b128 v[200:203], v178 offset:21504
	ds_read_b128 v[204:207], v178 offset:22528
	ds_read_b128 v[210:213], v178 offset:23552
	global_load_lds_dwordx4 v[170:171], off
	s_add_i32 m0, s82, 0x2000
	s_add_u32 s82, s80, 0x40000
	v_lshl_add_u64 v[214:215], s[80:81], 0, v[164:165]
	s_addc_u32 s83, s81, 0
	s_add_i32 s79, s79, s89
	global_load_lds_dwordx4 v[214:215], off
	v_lshl_add_u64 v[238:239], s[82:83], 0, v[208:209]
	s_mov_b32 m0, s79
	v_lshl_add_u64 v[244:245], s[84:85], 0, v[162:163]
	global_load_lds_dwordx4 v[238:239], off
	v_lshl_add_u64 v[238:239], s[82:83], 0, v[164:165]
	s_add_i32 m0, s79, 0x2000
	s_nop 0
	global_load_lds_dwordx4 v[238:239], off
	v_lshl_add_u64 v[238:239], s[84:85], 0, v[160:161]
	s_waitcnt vmcnt(6)
	s_waitcnt lgkmcnt(0)
	s_barrier
; #define PG8_STAGE(bufoff, gbase, voff) do { _Pragma("unroll") for (int _i = 0; _i < 2; ++_i) \
;         __builtin_amdgcn_global_load_lds((const unsigned*)((const char*)(gbase) + (voff)[_i]), (PG8_LAS unsigned*)(lds + (bufoff) + ldsw + _i * 8192), 16, 0, 0); } while (0)
; #define PG8_LDA(dst, b, h) do { _Pragma("unroll") for (int m = 0; m < 4; ++m) _Pragma("unroll") for (int k = 0; k < 2; ++k) dst[m][k] = *(const PG8_LAS bf16x8*)(lds + PG8_SA(b, h) + aoff + m * 2048 + k * 1024); } while (0)
; #define PG8_LDB(dst, b, h) do { _Pragma("unroll") for (int n = 0; n < 2; ++n) _Pragma("unroll") for (int k = 0; k < 2; ++k) dst[n][k] = *(const PG8_LAS bf16x8*)(lds + PG8_SB(b, h) + boff + n * 2048 + k * 1024); } while (0)
; #define PG8_MMA(ai, bj, At, Bt) do { __builtin_amdgcn_s_setprio(1); _Pragma("unroll") for (int m = 0; m < 4; ++m) _Pragma("unroll") for (int n = 0; n < 2; ++n) _Pragma("unroll") for (int k = 0; k < 2; ++k) \
;         acc[ai][bj][m][n] = __builtin_amdgcn_mfma_f32_16x16x32_bf16(Bt[n][k], At[m][k], acc[ai][bj][m][n], 0, 0, 0); __builtin_amdgcn_s_setprio(0); } while (0)
; #define PG8_WAIT_V(n) asm volatile("s_waitcnt vmcnt(" #n ")" ::: "memory")
; #define PG8_WAIT_L(n) asm volatile("s_waitcnt lgkmcnt(" #n ")" ::: "memory")
; #define PG8_BAR __builtin_amdgcn_s_barrier()
; #define PG8_SCHED __builtin_amdgcn_sched_barrier(0)
; template <class Epi, class Sched, bool ALIGN_EPI = false, bool SP2 = false, bool HALO = false>
; __device__ __forceinline__ void gemm_phase(PG8_LAS unsigned char* lds, const Gemm g, const Sched& S, const Epi& E, const int wave0) {
;     ...
;             PG8_WAIT_V(8); PG8_WAIT_L(0); PG8_BAR; PG8_MMA(1, 0, At, B0); PG8_MMA(1, 1, At, B1); PG8_BAR; PG8_SCHED;
;             PG8_LDB(B0, 1, 0); PG8_LDB(B1, 1, 1); PG8_SCHED; PG8_LDA(At, 1, 0); PG8_STAGE(PG8_SA(0, 1), a2 + hstepA, voffA);
;             PG8_WAIT_V(8); PG8_WAIT_L(0); PG8_BAR; PG8_MMA(0, 0, At, B0); PG8_MMA(0, 1, At, B1); PG8_BAR; PG8_SCHED;
	s_setprio 1
	s_waitcnt lgkmcnt(0)
	v_mfma_f32_16x16x32_bf16 v[72:75], v[56:59], v[180:183], v[72:75]
	v_mfma_f32_16x16x32_bf16 v[88:91], v[64:67], v[180:183], v[88:91]
	v_mfma_f32_16x16x32_bf16 v[44:47], v[56:59], v[188:191], v[44:47]
	v_mfma_f32_16x16x32_bf16 v[40:43], v[64:67], v[188:191], v[40:43]
	v_mfma_f32_16x16x32_bf16 v[28:31], v[56:59], v[196:199], v[28:31]
	v_mfma_f32_16x16x32_bf16 v[24:27], v[64:67], v[196:199], v[24:27]
	v_mfma_f32_16x16x32_bf16 v[12:15], v[56:59], v[204:207], v[12:15]
	v_mfma_f32_16x16x32_bf16 v[8:11], v[64:67], v[204:207], v[8:11]
	v_mfma_f32_16x16x32_bf16 v[72:75], v[60:63], v[184:187], v[72:75]
	v_mfma_f32_16x16x32_bf16 v[88:91], v[68:71], v[184:187], v[88:91]
	v_mfma_f32_16x16x32_bf16 v[44:47], v[60:63], v[192:195], v[44:47]
	v_mfma_f32_16x16x32_bf16 v[40:43], v[68:71], v[192:195], v[40:43]
	v_mfma_f32_16x16x32_bf16 v[28:31], v[60:63], v[200:203], v[28:31]
	v_mfma_f32_16x16x32_bf16 v[24:27], v[68:71], v[200:203], v[24:27]
	v_mfma_f32_16x16x32_bf16 v[12:15], v[60:63], v[210:213], v[12:15]
	v_mfma_f32_16x16x32_bf16 v[8:11], v[68:71], v[210:213], v[8:11]
	s_setprio 0
	s_setprio 1
	v_mfma_f32_16x16x32_bf16 v[52:55], v[76:79], v[180:183], v[52:55]
	v_mfma_f32_16x16x32_bf16 v[48:51], v[84:87], v[180:183], v[48:51]
	v_mfma_f32_16x16x32_bf16 v[36:39], v[76:79], v[188:191], v[36:39]
	v_mfma_f32_16x16x32_bf16 v[32:35], v[84:87], v[188:191], v[32:35]
	v_mfma_f32_16x16x32_bf16 v[20:23], v[76:79], v[196:199], v[20:23]
	v_mfma_f32_16x16x32_bf16 v[16:19], v[84:87], v[196:199], v[16:19]
	v_mfma_f32_16x16x32_bf16 v[4:7], v[76:79], v[204:207], v[4:7]
	v_mfma_f32_16x16x32_bf16 v[0:3], v[84:87], v[204:207], v[0:3]
	v_mfma_f32_16x16x32_bf16 v[52:55], v[80:83], v[184:187], v[52:55]
	v_mfma_f32_16x16x32_bf16 v[48:51], v[92:95], v[184:187], v[48:51]
	v_mfma_f32_16x16x32_bf16 v[36:39], v[80:83], v[192:195], v[36:39]
	v_mfma_f32_16x16x32_bf16 v[32:35], v[92:95], v[192:195], v[32:35]
	v_mfma_f32_16x16x32_bf16 v[20:23], v[80:83], v[200:203], v[20:23]
	v_mfma_f32_16x16x32_bf16 v[16:19], v[92:95], v[200:203], v[16:19]
	v_mfma_f32_16x16x32_bf16 v[4:7], v[80:83], v[210:213], v[4:7]
	v_mfma_f32_16x16x32_bf16 v[0:3], v[92:95], v[210:213], v[0:3]
	s_setprio 0
	s_barrier
	s_add_i32 s79, 0, 0x18000
	s_add_i32 s12, 0, 0x1c000
	v_add_u32_e32 v68, s79, v173
	v_add_u32_e32 v92, s12, v173
	ds_read_b128 v[56:59], v68
	ds_read_b128 v[60:63], v68 offset:1024
	ds_read_b128 v[64:67], v68 offset:2048
	ds_read_b128 v[68:71], v68 offset:3072
	ds_read_b128 v[76:79], v92
	ds_read_b128 v[80:83], v92 offset:1024
	ds_read_b128 v[84:87], v92 offset:2048
	ds_read_b128 v[92:95], v92 offset:3072
	s_add_u32 s82, s84, 0x3e000
	s_addc_u32 s83, s85, 0
	s_mov_b32 m0, s90
	s_nop 0
	global_load_lds_dwordx4 v[238:239], off
	s_mov_b32 m0, s91
	s_nop 0
	global_load_lds_dwordx4 v[244:245], off
	s_mov_b32 m0, s92
	v_lshl_add_u64 v[246:247], s[82:83], 0, v[160:161]
	ds_read_b128 v[180:183], v178 offset:32768
	ds_read_b128 v[184:187], v178 offset:33792
	ds_read_b128 v[188:191], v178 offset:34816
	ds_read_b128 v[192:195], v178 offset:35840
	ds_read_b128 v[196:199], v178 offset:36864
	ds_read_b128 v[200:203], v178 offset:37888
	ds_read_b128 v[204:207], v178 offset:38912
	ds_read_b128 v[210:213], v178 offset:39936
	global_load_lds_dwordx4 v[246:247], off
	v_lshl_add_u64 v[246:247], s[82:83], 0, v[162:163]
	s_mov_b32 m0, s93
	s_nop 0
	global_load_lds_dwordx4 v[246:247], off
	s_waitcnt vmcnt(8)
	s_waitcnt lgkmcnt(0)
	s_barrier
	s_setprio 1
	s_waitcnt lgkmcnt(0)
	v_mfma_f32_16x16x32_bf16 v[152:155], v[56:59], v[180:183], v[152:155]
	v_mfma_f32_16x16x32_bf16 v[156:159], v[64:67], v[180:183], v[156:159]
	v_mfma_f32_16x16x32_bf16 v[140:143], v[56:59], v[188:191], v[140:143]
	v_mfma_f32_16x16x32_bf16 v[136:139], v[64:67], v[188:191], v[136:139]
	v_mfma_f32_16x16x32_bf16 v[124:127], v[56:59], v[196:199], v[124:127]
	v_mfma_f32_16x16x32_bf16 v[120:123], v[64:67], v[196:199], v[120:123]
	v_mfma_f32_16x16x32_bf16 v[108:111], v[56:59], v[204:207], v[108:111]
	v_mfma_f32_16x16x32_bf16 v[104:107], v[64:67], v[204:207], v[104:107]
	v_mfma_f32_16x16x32_bf16 v[152:155], v[60:63], v[184:187], v[152:155]
	v_mfma_f32_16x16x32_bf16 v[156:159], v[68:71], v[184:187], v[156:159]
	v_mfma_f32_16x16x32_bf16 v[140:143], v[60:63], v[192:195], v[140:143]
	v_mfma_f32_16x16x32_bf16 v[136:139], v[68:71], v[192:195], v[136:139]
	v_mfma_f32_16x16x32_bf16 v[124:127], v[60:63], v[200:203], v[124:127]
	v_mfma_f32_16x16x32_bf16 v[120:123], v[68:71], v[200:203], v[120:123]
	v_mfma_f32_16x16x32_bf16 v[108:111], v[60:63], v[210:213], v[108:111]
	v_mfma_f32_16x16x32_bf16 v[104:107], v[68:71], v[210:213], v[104:107]
	s_setprio 0
	s_setprio 1
	v_mfma_f32_16x16x32_bf16 v[148:151], v[76:79], v[180:183], v[148:151]
	v_mfma_f32_16x16x32_bf16 v[144:147], v[84:87], v[180:183], v[144:147]
	v_mfma_f32_16x16x32_bf16 v[132:135], v[76:79], v[188:191], v[132:135]
	v_mfma_f32_16x16x32_bf16 v[128:131], v[84:87], v[188:191], v[128:131]
	v_mfma_f32_16x16x32_bf16 v[116:119], v[76:79], v[196:199], v[116:119]
	v_mfma_f32_16x16x32_bf16 v[112:115], v[84:87], v[196:199], v[112:115]
	v_mfma_f32_16x16x32_bf16 v[100:103], v[76:79], v[204:207], v[100:103]
	v_mfma_f32_16x16x32_bf16 v[96:99], v[84:87], v[204:207], v[96:99]
	v_mfma_f32_16x16x32_bf16 v[148:151], v[80:83], v[184:187], v[148:151]
	v_mfma_f32_16x16x32_bf16 v[144:147], v[92:95], v[184:187], v[144:147]
	v_mfma_f32_16x16x32_bf16 v[132:135], v[80:83], v[192:195], v[132:135]
	v_mfma_f32_16x16x32_bf16 v[128:131], v[92:95], v[192:195], v[128:131]
	v_mfma_f32_16x16x32_bf16 v[116:119], v[80:83], v[200:203], v[116:119]
	v_mfma_f32_16x16x32_bf16 v[112:115], v[92:95], v[200:203], v[112:115]
	v_mfma_f32_16x16x32_bf16 v[100:103], v[80:83], v[210:213], v[100:103]
	v_mfma_f32_16x16x32_bf16 v[96:99], v[92:95], v[210:213], v[96:99]
	s_setprio 0
	s_barrier
; #define PG8_STAGE(bufoff, gbase, voff) do { _Pragma("unroll") for (int _i = 0; _i < 2; ++_i) \
;         __builtin_amdgcn_global_load_lds((const unsigned*)((const char*)(gbase) + (voff)[_i]), (PG8_LAS unsigned*)(lds + (bufoff) + ldsw + _i * 8192), 16, 0, 0); } while (0)
; #define PG8_LDA(dst, b, h) do { _Pragma("unroll") for (int m = 0; m < 4; ++m) _Pragma("unroll") for (int k = 0; k < 2; ++k) dst[m][k] = *(const PG8_LAS bf16x8*)(lds + PG8_SA(b, h) + aoff + m * 2048 + k * 1024); } while (0)
; #define PG8_MMA(ai, bj, At, Bt) do { __builtin_amdgcn_s_setprio(1); _Pragma("unroll") for (int m = 0; m < 4; ++m) _Pragma("unroll") for (int n = 0; n < 2; ++n) _Pragma("unroll") for (int k = 0; k < 2; ++k) \
;         acc[ai][bj][m][n] = __builtin_amdgcn_mfma_f32_16x16x32_bf16(Bt[n][k], At[m][k], acc[ai][bj][m][n], 0, 0, 0); __builtin_amdgcn_s_setprio(0); } while (0)
; #define PG8_WAIT_V(n) asm volatile("s_waitcnt vmcnt(" #n ")" ::: "memory")
; #define PG8_WAIT_L(n) asm volatile("s_waitcnt lgkmcnt(" #n ")" ::: "memory")
; #define PG8_BAR __builtin_amdgcn_s_barrier()
; #define PG8_SCHED __builtin_amdgcn_sched_barrier(0)
; template <class Epi, class Sched, bool ALIGN_EPI = false, bool SP2 = false, bool HALO = false>
; __device__ __forceinline__ void gemm_phase(PG8_LAS unsigned char* lds, const Gemm g, const Sched& S, const Epi& E, const int wave0) {
;     ...
;         for (int t = 0; t < nt; t += 2) {
;     ...
;             PG8_WAIT_V(8); PG8_WAIT_L(0); PG8_BAR; PG8_MMA(0, 0, At, B0); PG8_MMA(0, 1, At, B1); PG8_BAR; PG8_SCHED;
;             PG8_LDA(At, 1, 1); PG8_STAGE(PG8_SB(1, 0), b3, voffB); PG8_STAGE(PG8_SB(1, 1), b3 + hstep, voffB); PG8_STAGE(PG8_SA(1, 0), a3, voffA);
;             PG8_WAIT_V(8); PG8_WAIT_L(0); PG8_BAR; PG8_MMA(1, 0, At, B0); PG8_MMA(1, 1, At, B1); PG8_BAR; PG8_SCHED;
;     ...
;         if constexpr (ALIGN_EPI) { if (wr == 0) PG8_BAR; }
	s_add_i32 s79, s79, s89
	v_lshl_add_u64 v[170:171], v[170:171], 0, s[20:21]
	s_mov_b32 m0, s79
	ds_read_b128 v[180:183], v178 offset:49152
	ds_read_b128 v[184:187], v178 offset:50176
	ds_read_b128 v[188:191], v178 offset:51200
	ds_read_b128 v[192:195], v178 offset:52224
	ds_read_b128 v[196:199], v178 offset:53248
	ds_read_b128 v[200:203], v178 offset:54272
	ds_read_b128 v[204:207], v178 offset:55296
	ds_read_b128 v[210:213], v178 offset:56320
	global_load_lds_dwordx4 v[170:171], off
	s_add_i32 m0, s79, 0x2000
	s_add_u32 s80, s80, 0x40080
	v_lshl_add_u64 v[170:171], v[214:215], 0, s[20:21]
	s_addc_u32 s81, s81, 0
	s_add_i32 s12, s12, s89
	global_load_lds_dwordx4 v[170:171], off
	v_lshl_add_u64 v[170:171], s[80:81], 0, v[208:209]
	s_mov_b32 m0, s12
	s_nop 0
	global_load_lds_dwordx4 v[170:171], off
	v_lshl_add_u64 v[170:171], s[80:81], 0, v[164:165]
	s_add_i32 m0, s12, 0x2000
	s_nop 0
	global_load_lds_dwordx4 v[170:171], off
	v_lshl_add_u64 v[170:171], v[238:239], 0, s[20:21]
	s_mov_b32 m0, s94
	s_nop 0
	global_load_lds_dwordx4 v[170:171], off
	v_lshl_add_u64 v[170:171], v[244:245], 0, s[20:21]
	s_mov_b32 m0, s95
	s_nop 0
	global_load_lds_dwordx4 v[170:171], off
	s_waitcnt vmcnt(8)
	s_waitcnt lgkmcnt(0)
	s_barrier
	s_setprio 1
	s_waitcnt lgkmcnt(0)
	v_mfma_f32_16x16x32_bf16 v[72:75], v[56:59], v[180:183], v[72:75]
	v_mfma_f32_16x16x32_bf16 v[88:91], v[64:67], v[180:183], v[88:91]
	v_mfma_f32_16x16x32_bf16 v[44:47], v[56:59], v[188:191], v[44:47]
	v_mfma_f32_16x16x32_bf16 v[40:43], v[64:67], v[188:191], v[40:43]
	v_mfma_f32_16x16x32_bf16 v[28:31], v[56:59], v[196:199], v[28:31]
	v_mfma_f32_16x16x32_bf16 v[24:27], v[64:67], v[196:199], v[24:27]
	v_mfma_f32_16x16x32_bf16 v[12:15], v[56:59], v[204:207], v[12:15]
	v_mfma_f32_16x16x32_bf16 v[8:11], v[64:67], v[204:207], v[8:11]
	v_mfma_f32_16x16x32_bf16 v[72:75], v[60:63], v[184:187], v[72:75]
	v_mfma_f32_16x16x32_bf16 v[88:91], v[68:71], v[184:187], v[88:91]
	v_mfma_f32_16x16x32_bf16 v[44:47], v[60:63], v[192:195], v[44:47]
	v_mfma_f32_16x16x32_bf16 v[40:43], v[68:71], v[192:195], v[40:43]
	v_mfma_f32_16x16x32_bf16 v[28:31], v[60:63], v[200:203], v[28:31]
	v_mfma_f32_16x16x32_bf16 v[24:27], v[68:71], v[200:203], v[24:27]
	v_mfma_f32_16x16x32_bf16 v[12:15], v[60:63], v[210:213], v[12:15]
	v_mfma_f32_16x16x32_bf16 v[8:11], v[68:71], v[210:213], v[8:11]
	s_setprio 0
	s_setprio 1
	v_mfma_f32_16x16x32_bf16 v[52:55], v[76:79], v[180:183], v[52:55]
	v_mfma_f32_16x16x32_bf16 v[48:51], v[84:87], v[180:183], v[48:51]
	v_mfma_f32_16x16x32_bf16 v[36:39], v[76:79], v[188:191], v[36:39]
	v_mfma_f32_16x16x32_bf16 v[32:35], v[84:87], v[188:191], v[32:35]
	v_mfma_f32_16x16x32_bf16 v[20:23], v[76:79], v[196:199], v[20:23]
	v_mfma_f32_16x16x32_bf16 v[16:19], v[84:87], v[196:199], v[16:19]
	v_mfma_f32_16x16x32_bf16 v[4:7], v[76:79], v[204:207], v[4:7]
	v_mfma_f32_16x16x32_bf16 v[0:3], v[84:87], v[204:207], v[0:3]
	v_mfma_f32_16x16x32_bf16 v[52:55], v[80:83], v[184:187], v[52:55]
	v_mfma_f32_16x16x32_bf16 v[48:51], v[92:95], v[184:187], v[48:51]
	v_mfma_f32_16x16x32_bf16 v[36:39], v[80:83], v[192:195], v[36:39]
	v_mfma_f32_16x16x32_bf16 v[32:35], v[92:95], v[192:195], v[32:35]
	v_mfma_f32_16x16x32_bf16 v[20:23], v[80:83], v[200:203], v[20:23]
	v_mfma_f32_16x16x32_bf16 v[16:19], v[92:95], v[200:203], v[16:19]
	v_mfma_f32_16x16x32_bf16 v[4:7], v[80:83], v[210:213], v[4:7]
	v_mfma_f32_16x16x32_bf16 v[0:3], v[92:95], v[210:213], v[0:3]
	s_setprio 0
	s_barrier
	s_add_i32 s78, s78, 2
	s_add_u32 vcc_lo, vcc_lo, 0x100
	s_addc_u32 vcc_hi, vcc_hi, 0
	s_add_u32 s48, s48, 0x100
	s_addc_u32 s49, s49, 0
	s_cmp_gt_u32 s78, 13
	s_cbranch_scc0 .LBB0_1081
	s_and_b64 vcc, exec, s[60:61]
	s_cbranch_vccz .LBB0_1084
	s_barrier
